# GDN scan: the 8 far-ahead A-operand loads (used two steps later) are issued after the next step's K/U/QK loads instead of before them, so urgent loads are not queued behind them
# baseline (speedup 1.0000x reference)
.LBB0_571:
	ds_read_b128 v[18:21], v0
	ds_read_b128 v[130:133], v0 offset:32
	ds_read_b128 v[134:137], v0 offset:64
	ds_read_b128 v[138:141], v0 offset:96
	ds_read_b128 v[142:145], v0 offset:128
	ds_read_b128 v[176:179], v0 offset:160
	ds_read_b128 v[180:183], v0 offset:192
	ds_read_b128 v[184:187], v0 offset:224
	s_add_i32 s38, s39, 2
	s_cmp_gt_u32 s39, 29
	s_cselect_b64 s[30:31], -1, 0
	s_cmp_lt_u32 s39, 30
	s_cselect_b32 s34, s38, 31
	v_add_u32_e32 v164, s34, v146
	s_waitcnt vmcnt(21) lgkmcnt(7)
	v_mfma_f32_32x32x16_bf16 v[18:33], v[34:37], v[18:21], 0
	s_waitcnt vmcnt(20) lgkmcnt(6)
	v_mfma_f32_32x32x16_bf16 v[18:33], v[38:41], v[130:133], v[18:33]
	s_waitcnt vmcnt(19) lgkmcnt(5)
	v_mfma_f32_32x32x16_bf16 v[18:33], v[42:45], v[134:137], v[18:33]
	s_waitcnt vmcnt(18) lgkmcnt(4)
	v_mfma_f32_32x32x16_bf16 v[18:33], v[46:49], v[138:141], v[18:33]
	s_waitcnt vmcnt(17) lgkmcnt(3)
	v_mfma_f32_32x32x16_bf16 v[18:33], v[50:53], v[142:145], v[18:33]
	s_waitcnt vmcnt(16) lgkmcnt(2)
	v_mfma_f32_32x32x16_bf16 v[18:33], v[54:57], v[176:179], v[18:33]
	s_waitcnt vmcnt(15) lgkmcnt(1)
	v_mfma_f32_32x32x16_bf16 v[18:33], v[58:61], v[180:183], v[18:33]
	s_waitcnt vmcnt(14) lgkmcnt(0)
	v_mfma_f32_32x32x16_bf16 v[18:33], v[62:65], v[184:187], v[18:33]
	v_readlane_b32 s34, v170, s39
	v_add_u32_e32 v175, 0x2000, v174
	s_and_saveexec_b64 s[36:37], s[0:1]
	s_cbranch_execz .LBB0_573
	s_waitcnt vmcnt(9)
	v_lshlrev_b32_e32 v130, 16, v122
	v_and_b32_e32 v131, 0xffff0000, v122
	v_lshlrev_b32_e32 v132, 16, v123
	v_and_b32_e32 v133, 0xffff0000, v123
	v_pk_add_f32 v[130:131], v[130:131], v[18:19] neg_lo:[0,1] neg_hi:[0,1]
	v_pk_add_f32 v[132:133], v[132:133], v[20:21] neg_lo:[0,1] neg_hi:[0,1]
	v_cvt_pk_bf16_f32 v130, v130, v131
	v_cvt_pk_bf16_f32 v131, v132, v133
	v_lshlrev_b32_e32 v132, 16, v124
	v_and_b32_e32 v133, 0xffff0000, v124
	v_lshlrev_b32_e32 v134, 16, v125
	v_and_b32_e32 v135, 0xffff0000, v125
	v_pk_add_f32 v[132:133], v[132:133], v[22:23] neg_lo:[0,1] neg_hi:[0,1]
	v_pk_add_f32 v[134:135], v[134:135], v[24:25] neg_lo:[0,1] neg_hi:[0,1]
	v_cvt_pk_bf16_f32 v132, v132, v133
	v_cvt_pk_bf16_f32 v133, v134, v135
	ds_write2_b64 v175, v[130:131], v[132:133] offset0:64 offset1:66
	s_waitcnt vmcnt(8)
	v_lshlrev_b32_e32 v130, 16, v126
	v_and_b32_e32 v131, 0xffff0000, v126
	v_lshlrev_b32_e32 v132, 16, v127
	v_and_b32_e32 v133, 0xffff0000, v127
	v_pk_add_f32 v[130:131], v[130:131], v[26:27] neg_lo:[0,1] neg_hi:[0,1]
	v_pk_add_f32 v[132:133], v[132:133], v[28:29] neg_lo:[0,1] neg_hi:[0,1]
	v_cvt_pk_bf16_f32 v130, v130, v131
	v_cvt_pk_bf16_f32 v131, v132, v133
	v_lshlrev_b32_e32 v132, 16, v128
	v_and_b32_e32 v133, 0xffff0000, v128
	v_lshlrev_b32_e32 v134, 16, v129
	v_and_b32_e32 v135, 0xffff0000, v129
	v_pk_add_f32 v[132:133], v[132:133], v[30:31] neg_lo:[0,1] neg_hi:[0,1]
	v_pk_add_f32 v[134:135], v[134:135], v[32:33] neg_lo:[0,1] neg_hi:[0,1]
	v_cvt_pk_bf16_f32 v132, v132, v133
	v_cvt_pk_bf16_f32 v133, v134, v135
	ds_write2_b64 v175, v[130:131], v[132:133] offset0:68 offset1:70

.LBB0_579:
	s_or_b64 exec, exec, s[34:35]
	s_waitcnt vmcnt(13)
	global_load_dwordx4 v[126:129], v[122:123], off
	s_nop 0
	global_load_dwordx4 v[122:125], v[124:125], off
	v_ashrrev_i32_e32 v165, 31, v164
	v_lshlrev_b64 v[34:35], 14, v[164:165]
	v_lshl_add_u64 v[50:51], v[148:149], 0, v[34:35]
	v_add_co_u32_e32 v62, vcc, 0x1000, v50
	global_load_dwordx4 v[34:37], v[50:51], off
	global_load_dwordx4 v[38:41], v[50:51], off offset:1024
	global_load_dwordx4 v[42:45], v[50:51], off offset:2048
	global_load_dwordx4 v[46:49], v[50:51], off offset:3072
	v_addc_co_u32_e32 v63, vcc, 0, v51, vcc
	global_load_dwordx4 v[50:53], v[62:63], off
	global_load_dwordx4 v[54:57], v[62:63], off offset:1024
	global_load_dwordx4 v[58:61], v[62:63], off offset:2048
	s_nop 0
	global_load_dwordx4 v[62:65], v[62:63], off offset:3072
	v_cvt_pk_bf16_f32 v130, v2, v3
	v_cvt_pk_bf16_f32 v131, v4, v5
	v_cvt_pk_bf16_f32 v132, v6, v7
	v_cvt_pk_bf16_f32 v133, v8, v9
	ds_write2_b64 v171, v[130:131], v[132:133] offset1:2
	v_cvt_pk_bf16_f32 v130, v10, v11
	v_cvt_pk_bf16_f32 v131, v12, v13
	v_cvt_pk_bf16_f32 v132, v14, v15
	v_cvt_pk_bf16_f32 v133, v16, v17
	v_lshl_add_u64 v[164:165], s[80:81], 0, v[156:157]
	ds_write2_b64 v171, v[130:131], v[132:133] offset0:4 offset1:6
	s_and_saveexec_b64 s[34:35], s[2:3]
	s_cbranch_execz .LBB0_581
	v_add_co_u32_e32 v130, vcc, 0x2000000, v164
	v_cvt_pk_bf16_f32 v18, v18, s0
	s_nop 0
	v_addc_co_u32_e32 v131, vcc, 0, v165, vcc
	global_store_short v[130:131], v18, off
	v_cvt_pk_bf16_f32 v18, v19, s0
	global_store_short v[130:131], v18, off offset:1024
	v_cvt_pk_bf16_f32 v18, v20, s0
	global_store_short v[130:131], v18, off offset:2048
	v_cvt_pk_bf16_f32 v18, v21, s0
	global_store_short v[130:131], v18, off offset:3072
	v_add_co_u32_e32 v18, vcc, s41, v164
	v_cvt_pk_bf16_f32 v20, v22, s0
	s_nop 0
	v_addc_co_u32_e32 v19, vcc, 0, v165, vcc
	global_store_short v[18:19], v20, off
	v_cvt_pk_bf16_f32 v20, v23, s0
	global_store_short v[18:19], v20, off offset:1024
	v_cvt_pk_bf16_f32 v20, v24, s0
	global_store_short v[18:19], v20, off offset:2048
	v_cvt_pk_bf16_f32 v20, v25, s0
	global_store_short v[18:19], v20, off offset:3072
	v_add_co_u32_e32 v18, vcc, s42, v164
	v_cvt_pk_bf16_f32 v20, v26, s0
	s_nop 0
	v_addc_co_u32_e32 v19, vcc, 0, v165, vcc
	global_store_short v[18:19], v20, off
	v_cvt_pk_bf16_f32 v20, v27, s0
	global_store_short v[18:19], v20, off offset:1024
	v_cvt_pk_bf16_f32 v20, v28, s0
	global_store_short v[18:19], v20, off offset:2048
	v_cvt_pk_bf16_f32 v20, v29, s0
	global_store_short v[18:19], v20, off offset:3072
	v_add_co_u32_e32 v18, vcc, 0x2006000, v164
	v_cvt_pk_bf16_f32 v20, v30, s0
	s_nop 0
	v_addc_co_u32_e32 v19, vcc, 0, v165, vcc
	global_store_short v[18:19], v20, off
	v_cvt_pk_bf16_f32 v20, v31, s0
	global_store_short v[18:19], v20, off offset:1024
	v_cvt_pk_bf16_f32 v20, v32, s0
	global_store_short v[18:19], v20, off offset:2048
	v_cvt_pk_bf16_f32 v20, v33, s0
	global_store_short v[18:19], v20, off offset:3072
.LBB0_581:
	s_or_b64 exec, exec, s[34:35]
	s_waitcnt lgkmcnt(0)
	s_barrier
	ds_read_b128 v[18:21], v0
	ds_read_b128 v[130:133], v0 offset:32
	ds_read_b128 v[134:137], v0 offset:64
	ds_read_b128 v[138:141], v0 offset:96
	ds_read_b128 v[142:145], v0 offset:128
	ds_read_b128 v[176:179], v0 offset:160
	ds_read_b128 v[180:183], v0 offset:192
	ds_read_b128 v[184:187], v0 offset:224
	s_add_i32 s34, s39, 1
	s_min_u32 s35, s39, 28
	v_add_u32_e32 v188, s35, v173
	s_waitcnt vmcnt(21) lgkmcnt(7)
	v_mfma_f32_32x32x16_bf16 v[18:33], v[74:77], v[18:21], 0
	s_waitcnt vmcnt(20) lgkmcnt(6)
	v_mfma_f32_32x32x16_bf16 v[18:33], v[78:81], v[130:133], v[18:33]
	s_waitcnt vmcnt(19) lgkmcnt(5)
	v_mfma_f32_32x32x16_bf16 v[18:33], v[82:85], v[134:137], v[18:33]
	s_waitcnt vmcnt(18) lgkmcnt(4)
	v_mfma_f32_32x32x16_bf16 v[18:33], v[86:89], v[138:141], v[18:33]
	s_waitcnt vmcnt(17) lgkmcnt(3)
	v_mfma_f32_32x32x16_bf16 v[18:33], v[90:93], v[142:145], v[18:33]
	s_waitcnt vmcnt(16) lgkmcnt(2)
	v_mfma_f32_32x32x16_bf16 v[18:33], v[94:97], v[176:179], v[18:33]
	s_waitcnt vmcnt(15) lgkmcnt(1)
	v_mfma_f32_32x32x16_bf16 v[18:33], v[98:101], v[180:183], v[18:33]
	s_waitcnt vmcnt(14) lgkmcnt(0)
	v_mfma_f32_32x32x16_bf16 v[18:33], v[102:105], v[184:187], v[18:33]
	v_readlane_b32 s34, v170, s34
	s_and_saveexec_b64 s[36:37], s[0:1]
	s_cbranch_execz .LBB0_583
	s_waitcnt vmcnt(9)
	v_lshlrev_b32_e32 v130, 16, v126
	v_and_b32_e32 v131, 0xffff0000, v126
	v_lshlrev_b32_e32 v132, 16, v127
	v_and_b32_e32 v133, 0xffff0000, v127
	v_pk_add_f32 v[130:131], v[130:131], v[18:19] neg_lo:[0,1] neg_hi:[0,1]
	v_pk_add_f32 v[132:133], v[132:133], v[20:21] neg_lo:[0,1] neg_hi:[0,1]
	v_cvt_pk_bf16_f32 v130, v130, v131
	v_cvt_pk_bf16_f32 v131, v132, v133
	v_lshlrev_b32_e32 v132, 16, v128
	v_and_b32_e32 v133, 0xffff0000, v128
	v_lshlrev_b32_e32 v134, 16, v129
	v_and_b32_e32 v135, 0xffff0000, v129
	v_pk_add_f32 v[132:133], v[132:133], v[22:23] neg_lo:[0,1] neg_hi:[0,1]
	v_pk_add_f32 v[134:135], v[134:135], v[24:25] neg_lo:[0,1] neg_hi:[0,1]
	v_cvt_pk_bf16_f32 v132, v132, v133
	v_cvt_pk_bf16_f32 v133, v134, v135
	ds_write2_b64 v175, v[130:131], v[132:133] offset0:64 offset1:66
	s_waitcnt vmcnt(8)
	v_lshlrev_b32_e32 v130, 16, v122
	v_and_b32_e32 v131, 0xffff0000, v122
	v_lshlrev_b32_e32 v132, 16, v123
	v_and_b32_e32 v133, 0xffff0000, v123
	v_pk_add_f32 v[130:131], v[130:131], v[26:27] neg_lo:[0,1] neg_hi:[0,1]
	v_pk_add_f32 v[132:133], v[132:133], v[28:29] neg_lo:[0,1] neg_hi:[0,1]
	v_cvt_pk_bf16_f32 v130, v130, v131
	v_cvt_pk_bf16_f32 v131, v132, v133
	v_lshlrev_b32_e32 v132, 16, v124
	v_and_b32_e32 v133, 0xffff0000, v124
	v_lshlrev_b32_e32 v134, 16, v125
	v_and_b32_e32 v135, 0xffff0000, v125
	v_pk_add_f32 v[132:133], v[132:133], v[30:31] neg_lo:[0,1] neg_hi:[0,1]
	v_pk_add_f32 v[134:135], v[134:135], v[32:33] neg_lo:[0,1] neg_hi:[0,1]
	v_cvt_pk_bf16_f32 v132, v132, v133
	v_cvt_pk_bf16_f32 v133, v134, v135
	ds_write2_b64 v175, v[130:131], v[132:133] offset0:68 offset1:70

.LBB0_587:
	s_andn2_saveexec_b64 s[34:35], s[34:35]
	v_lshl_add_u64 v[122:123], v[124:125], 1, v[154:155]
	v_lshl_add_u64 v[126:127], v[122:123], 0, 16
	s_or_b64 exec, exec, s[34:35]
	global_load_dwordx4 v[122:125], v[122:123], off
	s_nop 0
	global_load_dwordx4 v[126:129], v[126:127], off
	v_ashrrev_i32_e32 v189, 31, v188
	v_lshlrev_b64 v[74:75], 14, v[188:189]
	v_lshl_add_u64 v[90:91], v[148:149], 0, v[74:75]
	v_add_co_u32_e32 v102, vcc, 0x1000, v90
	global_load_dwordx4 v[74:77], v[90:91], off
	global_load_dwordx4 v[78:81], v[90:91], off offset:1024
	global_load_dwordx4 v[82:85], v[90:91], off offset:2048
	global_load_dwordx4 v[86:89], v[90:91], off offset:3072
	v_addc_co_u32_e32 v103, vcc, 0, v91, vcc
	global_load_dwordx4 v[90:93], v[102:103], off
	global_load_dwordx4 v[94:97], v[102:103], off offset:1024
	global_load_dwordx4 v[98:101], v[102:103], off offset:2048
	s_nop 0
	global_load_dwordx4 v[102:105], v[102:103], off offset:3072
	v_cvt_pk_bf16_f32 v130, v2, v3
	v_cvt_pk_bf16_f32 v131, v4, v5
	v_cvt_pk_bf16_f32 v132, v6, v7
	v_cvt_pk_bf16_f32 v133, v8, v9
	ds_write2_b64 v171, v[130:131], v[132:133] offset1:2
	v_cvt_pk_bf16_f32 v130, v10, v11
	v_cvt_pk_bf16_f32 v131, v12, v13
	v_cvt_pk_bf16_f32 v132, v14, v15
	v_cvt_pk_bf16_f32 v133, v16, v17
	ds_write2_b64 v171, v[130:131], v[132:133] offset0:4 offset1:6
	s_and_saveexec_b64 s[34:35], s[2:3]
	s_cbranch_execz .LBB0_570
	v_add_co_u32_e32 v130, vcc, 0x2010000, v164
	v_cvt_pk_bf16_f32 v18, v18, s0
	s_nop 0
	v_addc_co_u32_e32 v131, vcc, 0, v165, vcc
	global_store_short v[130:131], v18, off
	v_cvt_pk_bf16_f32 v18, v19, s0
	global_store_short v[130:131], v18, off offset:1024
	v_cvt_pk_bf16_f32 v18, v20, s0
	global_store_short v[130:131], v18, off offset:2048
	v_cvt_pk_bf16_f32 v18, v21, s0
	global_store_short v[130:131], v18, off offset:3072
	v_add_co_u32_e32 v18, vcc, s43, v164
	v_cvt_pk_bf16_f32 v20, v22, s0
	s_nop 0
	v_addc_co_u32_e32 v19, vcc, 0, v165, vcc
	global_store_short v[18:19], v20, off
	v_cvt_pk_bf16_f32 v20, v23, s0
	global_store_short v[18:19], v20, off offset:1024
	v_cvt_pk_bf16_f32 v20, v24, s0
	global_store_short v[18:19], v20, off offset:2048
	v_cvt_pk_bf16_f32 v20, v25, s0
	global_store_short v[18:19], v20, off offset:3072
	v_add_co_u32_e32 v18, vcc, s46, v164
	v_cvt_pk_bf16_f32 v20, v26, s0
	s_nop 0
	v_addc_co_u32_e32 v19, vcc, 0, v165, vcc
	global_store_short v[18:19], v20, off
	v_cvt_pk_bf16_f32 v20, v27, s0
	global_store_short v[18:19], v20, off offset:1024
	v_cvt_pk_bf16_f32 v20, v28, s0
	global_store_short v[18:19], v20, off offset:2048
	v_cvt_pk_bf16_f32 v20, v29, s0
	global_store_short v[18:19], v20, off offset:3072
	v_add_co_u32_e32 v18, vcc, 0x2016000, v164
	v_cvt_pk_bf16_f32 v20, v30, s0
	s_nop 0
	v_addc_co_u32_e32 v19, vcc, 0, v165, vcc
	global_store_short v[18:19], v20, off
	v_cvt_pk_bf16_f32 v20, v31, s0
	global_store_short v[18:19], v20, off offset:1024
	v_cvt_pk_bf16_f32 v20, v32, s0
	global_store_short v[18:19], v20, off offset:2048
	v_cvt_pk_bf16_f32 v20, v33, s0
	global_store_short v[18:19], v20, off offset:3072
	s_branch .LBB0_570
